# MLA loops: LDS-DMA issue groups moved from the step head into transcendental-only MFMA gaps (4-slot ring gives the loads two steps of slack)
# baseline (speedup 1.0000x reference)
.LmlaL_top:
	v_add_u32_e32 v164, s15, v238
	v_add_u32_e32 v165, s4, v238
	ds_read_b128 v[172:175], v164
	ds_read_b128 v[176:179], v164 offset:512
	ds_read_b128 v[180:183], v164 offset:2048
	ds_read_b128 v[184:187], v164 offset:2560
	ds_read_b128 v[188:191], v164 offset:4096
	s_cmp_eq_u32 s19, -2
	s_cselect_b64 s[6:7], -1, 0
	v_cmp_lt_f32_e32 vcc, s33, v162
	s_or_b64 vcc, s[6:7], vcc
	s_cbranch_vccz .LmlaLA_common
	v_mov_b32_e32 v163, v162
	s_nop 1
	v_permlane32_swap_b32_e32 v162, v163
	v_max_f32_e32 v162, v162, v163
	v_max_f32_e32 v220, 0, v162
	v_cndmask_b32_e64 v220, v220, v162, s[6:7]
	v_exp_f32_e64 v222, -v220
	v_add_f32_e32 v239, v239, v220
	v_pk_add_f32 v[66:67], v[66:67], v[220:221] op_sel_hi:[1,0] neg_lo:[0,1] neg_hi:[0,1]
	v_pk_add_f32 v[68:69], v[68:69], v[220:221] op_sel_hi:[1,0] neg_lo:[0,1] neg_hi:[0,1]
	v_pk_add_f32 v[70:71], v[70:71], v[220:221] op_sel_hi:[1,0] neg_lo:[0,1] neg_hi:[0,1]
	v_pk_add_f32 v[72:73], v[72:73], v[220:221] op_sel_hi:[1,0] neg_lo:[0,1] neg_hi:[0,1]
	v_pk_add_f32 v[74:75], v[74:75], v[220:221] op_sel_hi:[1,0] neg_lo:[0,1] neg_hi:[0,1]
	v_pk_add_f32 v[76:77], v[76:77], v[220:221] op_sel_hi:[1,0] neg_lo:[0,1] neg_hi:[0,1]
	v_pk_add_f32 v[78:79], v[78:79], v[220:221] op_sel_hi:[1,0] neg_lo:[0,1] neg_hi:[0,1]
	v_pk_add_f32 v[80:81], v[80:81], v[220:221] op_sel_hi:[1,0] neg_lo:[0,1] neg_hi:[0,1]
	v_pk_add_f32 v[50:51], v[50:51], v[220:221] op_sel_hi:[1,0] neg_lo:[0,1] neg_hi:[0,1]
	v_pk_add_f32 v[52:53], v[52:53], v[220:221] op_sel_hi:[1,0] neg_lo:[0,1] neg_hi:[0,1]
	v_pk_add_f32 v[54:55], v[54:55], v[220:221] op_sel_hi:[1,0] neg_lo:[0,1] neg_hi:[0,1]
	v_pk_add_f32 v[56:57], v[56:57], v[220:221] op_sel_hi:[1,0] neg_lo:[0,1] neg_hi:[0,1]
	v_pk_add_f32 v[58:59], v[58:59], v[220:221] op_sel_hi:[1,0] neg_lo:[0,1] neg_hi:[0,1]
	v_pk_add_f32 v[60:61], v[60:61], v[220:221] op_sel_hi:[1,0] neg_lo:[0,1] neg_hi:[0,1]
	v_pk_add_f32 v[62:63], v[62:63], v[220:221] op_sel_hi:[1,0] neg_lo:[0,1] neg_hi:[0,1]
	v_pk_add_f32 v[64:65], v[64:65], v[220:221] op_sel_hi:[1,0] neg_lo:[0,1] neg_hi:[0,1]
	v_pk_mul_f32 v[2:3], v[2:3], v[222:223] op_sel_hi:[1,0]
	v_pk_mul_f32 v[4:5], v[4:5], v[222:223] op_sel_hi:[1,0]
	v_pk_mul_f32 v[6:7], v[6:7], v[222:223] op_sel_hi:[1,0]
	v_pk_mul_f32 v[8:9], v[8:9], v[222:223] op_sel_hi:[1,0]
	v_pk_mul_f32 v[10:11], v[10:11], v[222:223] op_sel_hi:[1,0]
	v_pk_mul_f32 v[12:13], v[12:13], v[222:223] op_sel_hi:[1,0]
	v_pk_mul_f32 v[14:15], v[14:15], v[222:223] op_sel_hi:[1,0]
	v_pk_mul_f32 v[16:17], v[16:17], v[222:223] op_sel_hi:[1,0]
	v_pk_mul_f32 v[18:19], v[18:19], v[222:223] op_sel_hi:[1,0]
	v_pk_mul_f32 v[20:21], v[20:21], v[222:223] op_sel_hi:[1,0]
	v_pk_mul_f32 v[22:23], v[22:23], v[222:223] op_sel_hi:[1,0]
	v_pk_mul_f32 v[24:25], v[24:25], v[222:223] op_sel_hi:[1,0]
	v_pk_mul_f32 v[26:27], v[26:27], v[222:223] op_sel_hi:[1,0]
	v_pk_mul_f32 v[28:29], v[28:29], v[222:223] op_sel_hi:[1,0]
	v_pk_mul_f32 v[30:31], v[30:31], v[222:223] op_sel_hi:[1,0]
	v_pk_mul_f32 v[32:33], v[32:33], v[222:223] op_sel_hi:[1,0]
	v_mul_f32_e32 v170, v170, v222
	v_xor_b32_e32 v82, 0x80000000, v239
	v_mov_b32_e32 v83, v82
	v_mov_b32_e32 v84, v82
	v_mov_b32_e32 v85, v82
	v_mov_b32_e32 v86, v82
	v_mov_b32_e32 v87, v82
	v_mov_b32_e32 v88, v82
	v_mov_b32_e32 v89, v82
	v_mov_b32_e32 v90, v82
	v_mov_b32_e32 v91, v82
	v_mov_b32_e32 v92, v82
	v_mov_b32_e32 v93, v82
	v_mov_b32_e32 v94, v82
	v_mov_b32_e32 v95, v82
	v_mov_b32_e32 v96, v82
	v_mov_b32_e32 v97, v82
	s_nop 1
.LmlaLA_common:
	s_waitcnt lgkmcnt(4)
	v_mfma_f32_32x32x16_bf16 v[98:113], v[172:175], v[150:153], v[82:97]
	ds_read_b128 v[192:195], v164 offset:4608
	s_add_i32 s24, s14, s20
	s_mov_b32 m0, s24
	s_add_u32 s28, s28, 0
	global_load_lds_dwordx4 v154, s[34:35]
	s_add_u32 s34, s34, 0x10000
	s_addc_u32 s35, s35, 0
	v_exp_f32_e32 v66, v66
	v_exp_f32_e32 v67, v67
	v_exp_f32_e32 v68, v68
	s_waitcnt lgkmcnt(4)
	v_mfma_f32_32x32x16_bf16 v[114:129], v[176:179], v[150:153], v[82:97]
	ds_read_b128 v[240:243], v164 offset:6144
	s_add_i32 m0, s24, 0x3000
	s_andn2_b64 vcc, exec, s[16:17]
	global_load_lds_dwordx4 v156, s[28:29]
	s_add_u32 s28, s28, 0x80
	s_addc_u32 s29, s29, 0
	v_exp_f32_e32 v69, v69
	v_exp_f32_e32 v70, v70
	v_exp_f32_e32 v71, v71
	s_waitcnt lgkmcnt(4)
	v_mfma_f32_32x32x16_bf16 v[98:113], v[180:183], v[134:137], v[98:113]
	ds_read_b128 v[244:247], v164 offset:6656
	v_exp_f32_e32 v72, v72
	v_exp_f32_e32 v73, v73
	v_cvt_pk_bf16_f32 v34, v66, v67
	v_cvt_pk_bf16_f32 v35, v68, v69
	s_waitcnt lgkmcnt(4)
	v_mfma_f32_32x32x16_bf16 v[114:129], v[184:187], v[134:137], v[114:129]
	ds_read_b128 v[248:251], v164 offset:8192
	v_exp_f32_e32 v74, v74
	v_exp_f32_e32 v75, v75
	v_cvt_pk_bf16_f32 v36, v70, v71
	v_cvt_pk_bf16_f32 v37, v72, v73
	s_waitcnt lgkmcnt(4)
	v_mfma_f32_32x32x16_bf16 v[98:113], v[188:191], v[138:141], v[98:113]
	ds_read_b128 v[172:175], v164 offset:8704
	s_andn2_b64 vcc, exec, s[16:17]
	s_cbranch_vccnz .LmlaLA_nokr
	s_add_i32 m0, s24, 0x2000
	s_nop 0
	global_load_lds_dwordx4 v158, s[38:39]
.LmlaLA_nokr:
	s_add_u32 s38, s38, 0x10000
	s_addc_u32 s39, s39, 0
	v_exp_f32_e32 v76, v76
	v_exp_f32_e32 v77, v77
	v_exp_f32_e32 v78, v78
	s_waitcnt lgkmcnt(4)
	v_mfma_f32_32x32x16_bf16 v[114:129], v[192:195], v[138:141], v[114:129]
	ds_read_b128 v[176:179], v164 offset:10240
	v_exp_f32_e32 v79, v79
	v_exp_f32_e32 v80, v80
	v_exp_f32_e32 v81, v81
	s_waitcnt lgkmcnt(4)
	v_mfma_f32_32x32x16_bf16 v[98:113], v[240:243], v[142:145], v[98:113]
	ds_read_b128 v[180:183], v164 offset:10752
	v_exp_f32_e32 v50, v50
	v_exp_f32_e32 v51, v51
	v_cvt_pk_bf16_f32 v38, v74, v75
	v_cvt_pk_bf16_f32 v39, v76, v77
	s_waitcnt lgkmcnt(4)
	v_mfma_f32_32x32x16_bf16 v[114:129], v[244:247], v[142:145], v[114:129]
	ds_read_b128 v[184:187], v165 offset:12288
	v_exp_f32_e32 v52, v52
	v_exp_f32_e32 v53, v53
	v_cvt_pk_bf16_f32 v40, v78, v79
	v_cvt_pk_bf16_f32 v41, v80, v81
	s_waitcnt lgkmcnt(4)
	v_mfma_f32_32x32x16_bf16 v[98:113], v[248:251], v[146:149], v[98:113]
	ds_read_b128 v[188:191], v165 offset:12800
	v_exp_f32_e32 v54, v54
	v_exp_f32_e32 v55, v55
	v_exp_f32_e32 v56, v56
	s_waitcnt lgkmcnt(4)
	v_mfma_f32_32x32x16_bf16 v[114:129], v[172:175], v[146:149], v[114:129]
	ds_read_b128 v[192:195], v165 offset:14336
	v_exp_f32_e32 v57, v57
	v_exp_f32_e32 v58, v58
	v_cvt_pk_bf16_f32 v42, v50, v51
	v_cvt_pk_bf16_f32 v43, v52, v53
	s_waitcnt lgkmcnt(4)
	v_mfma_f32_32x32x16_bf16 v[98:113], v[176:179], v[130:133], v[98:113]
	ds_read_b128 v[240:243], v165 offset:14848
	v_exp_f32_e32 v59, v59
	v_exp_f32_e32 v60, v60
	v_cvt_pk_bf16_f32 v44, v54, v55
	v_cvt_pk_bf16_f32 v45, v56, v57
	s_waitcnt lgkmcnt(4)
	v_mfma_f32_32x32x16_bf16 v[114:129], v[180:183], v[130:133], v[114:129]
	ds_read_b128 v[244:247], v165 offset:16384
	v_exp_f32_e32 v61, v61
	v_exp_f32_e32 v62, v62
	v_exp_f32_e32 v63, v63
	s_waitcnt lgkmcnt(4)
	v_mfma_f32_32x32x16_bf16 v[2:17], v[184:187], v[34:37], v[2:17]
	ds_read_b128 v[248:251], v165 offset:16896
	v_exp_f32_e32 v64, v64
	v_exp_f32_e32 v65, v65
	v_cvt_pk_bf16_f32 v46, v58, v59
	v_cvt_pk_bf16_f32 v47, v60, v61
	s_waitcnt lgkmcnt(4)
	v_mfma_f32_32x32x16_bf16 v[18:33], v[188:191], v[34:37], v[18:33]
	ds_read_b128 v[172:175], v165 offset:18432
	v_cvt_pk_bf16_f32 v48, v62, v63
	v_cvt_pk_bf16_f32 v49, v64, v65
	v_add_f32_e32 v166, v66, v67
	v_add_f32_e32 v167, v68, v69
	v_add_f32_e32 v168, v70, v71
	v_add_f32_e32 v169, v72, v73
	s_waitcnt lgkmcnt(4)
	v_mfma_f32_32x32x16_bf16 v[2:17], v[192:195], v[38:41], v[2:17]
	ds_read_b128 v[176:179], v165 offset:18944
	v_add_f32_e32 v166, v166, v74
	v_add_f32_e32 v167, v167, v75
	v_add_f32_e32 v168, v168, v76
	v_add_f32_e32 v169, v169, v77
	v_max3_f32 v162, v98, v99, v100
	v_max3_f32 v163, v114, v115, v116
	s_waitcnt lgkmcnt(4)
	v_mfma_f32_32x32x16_bf16 v[18:33], v[240:243], v[38:41], v[18:33]
	v_add_f32_e32 v166, v166, v78
	v_add_f32_e32 v167, v167, v79
	v_add_f32_e32 v168, v168, v80
	v_add_f32_e32 v169, v169, v81
	v_max3_f32 v162, v162, v101, v102
	v_max3_f32 v163, v163, v117, v118
	s_waitcnt lgkmcnt(3)
	v_mfma_f32_32x32x16_bf16 v[2:17], v[244:247], v[42:45], v[2:17]
	v_add_f32_e32 v166, v166, v50
	v_add_f32_e32 v167, v167, v51
	v_add_f32_e32 v168, v168, v52
	v_add_f32_e32 v169, v169, v53
	v_max3_f32 v162, v162, v103, v104
	v_max3_f32 v163, v163, v119, v120
	s_waitcnt lgkmcnt(2)
	v_mfma_f32_32x32x16_bf16 v[18:33], v[248:251], v[42:45], v[18:33]
	v_add_f32_e32 v166, v166, v54
	v_add_f32_e32 v167, v167, v55
	v_add_f32_e32 v168, v168, v56
	v_add_f32_e32 v169, v169, v57
	v_max3_f32 v162, v162, v105, v106
	v_max3_f32 v163, v163, v121, v122
	s_waitcnt lgkmcnt(1)
	v_mfma_f32_32x32x16_bf16 v[2:17], v[172:175], v[46:49], v[2:17]
	v_add_f32_e32 v166, v166, v58
	v_add_f32_e32 v167, v167, v59
	v_add_f32_e32 v168, v168, v60
	v_add_f32_e32 v169, v169, v61
	v_max3_f32 v162, v162, v107, v108
	v_max3_f32 v163, v163, v123, v124
	s_waitcnt lgkmcnt(0)
	v_mfma_f32_32x32x16_bf16 v[18:33], v[176:179], v[46:49], v[18:33]
	v_add_f32_e32 v166, v166, v62
	v_add_f32_e32 v167, v167, v63
	v_add_f32_e32 v168, v168, v64
	v_add_f32_e32 v169, v169, v65
	v_max3_f32 v162, v162, v109, v110
	v_max3_f32 v163, v163, v125, v126
	v_max3_f32 v162, v162, v111, v112
	v_max3_f32 v163, v163, v127, v128
	v_add_f32_e32 v166, v166, v167
	v_add_f32_e32 v168, v168, v169
	v_add_f32_e32 v166, v166, v168
	v_add_f32_e32 v170, v170, v166
	v_max3_f32 v162, v162, v113, v129
	v_max_f32_e32 v162, v162, v163
	s_andn2_b64 vcc, exec, s[16:17]
	s_cbranch_vccnz .LmlaLA_w2
	s_waitcnt vmcnt(3)
	s_branch .LmlaLA_wd

.LmlaLA_wd:
	s_barrier
	v_add_u32_e32 v164, s18, v238
	v_add_u32_e32 v165, s15, v238
	ds_read_b128 v[172:175], v164
	ds_read_b128 v[176:179], v164 offset:512
	ds_read_b128 v[180:183], v164 offset:2048
	ds_read_b128 v[184:187], v164 offset:2560
	ds_read_b128 v[188:191], v164 offset:4096
	v_cmp_lt_f32_e32 vcc, s33, v162
	s_cbranch_vccz .LmlaLB_common
	v_mov_b32_e32 v163, v162
	s_nop 1
	v_permlane32_swap_b32_e32 v162, v163
	v_max_f32_e32 v162, v162, v163
	v_max_f32_e32 v220, 0, v162
	v_exp_f32_e64 v222, -v220
	v_add_f32_e32 v239, v239, v220
	v_pk_add_f32 v[98:99], v[98:99], v[220:221] op_sel_hi:[1,0] neg_lo:[0,1] neg_hi:[0,1]
	v_pk_add_f32 v[100:101], v[100:101], v[220:221] op_sel_hi:[1,0] neg_lo:[0,1] neg_hi:[0,1]
	v_pk_add_f32 v[102:103], v[102:103], v[220:221] op_sel_hi:[1,0] neg_lo:[0,1] neg_hi:[0,1]
	v_pk_add_f32 v[104:105], v[104:105], v[220:221] op_sel_hi:[1,0] neg_lo:[0,1] neg_hi:[0,1]
	v_pk_add_f32 v[106:107], v[106:107], v[220:221] op_sel_hi:[1,0] neg_lo:[0,1] neg_hi:[0,1]
	v_pk_add_f32 v[108:109], v[108:109], v[220:221] op_sel_hi:[1,0] neg_lo:[0,1] neg_hi:[0,1]
	v_pk_add_f32 v[110:111], v[110:111], v[220:221] op_sel_hi:[1,0] neg_lo:[0,1] neg_hi:[0,1]
	v_pk_add_f32 v[112:113], v[112:113], v[220:221] op_sel_hi:[1,0] neg_lo:[0,1] neg_hi:[0,1]
	v_pk_add_f32 v[114:115], v[114:115], v[220:221] op_sel_hi:[1,0] neg_lo:[0,1] neg_hi:[0,1]
	v_pk_add_f32 v[116:117], v[116:117], v[220:221] op_sel_hi:[1,0] neg_lo:[0,1] neg_hi:[0,1]
	v_pk_add_f32 v[118:119], v[118:119], v[220:221] op_sel_hi:[1,0] neg_lo:[0,1] neg_hi:[0,1]
	v_pk_add_f32 v[120:121], v[120:121], v[220:221] op_sel_hi:[1,0] neg_lo:[0,1] neg_hi:[0,1]
	v_pk_add_f32 v[122:123], v[122:123], v[220:221] op_sel_hi:[1,0] neg_lo:[0,1] neg_hi:[0,1]
	v_pk_add_f32 v[124:125], v[124:125], v[220:221] op_sel_hi:[1,0] neg_lo:[0,1] neg_hi:[0,1]
	v_pk_add_f32 v[126:127], v[126:127], v[220:221] op_sel_hi:[1,0] neg_lo:[0,1] neg_hi:[0,1]
	v_pk_add_f32 v[128:129], v[128:129], v[220:221] op_sel_hi:[1,0] neg_lo:[0,1] neg_hi:[0,1]
	v_pk_mul_f32 v[2:3], v[2:3], v[222:223] op_sel_hi:[1,0]
	v_pk_mul_f32 v[4:5], v[4:5], v[222:223] op_sel_hi:[1,0]
	v_pk_mul_f32 v[6:7], v[6:7], v[222:223] op_sel_hi:[1,0]
	v_pk_mul_f32 v[8:9], v[8:9], v[222:223] op_sel_hi:[1,0]
	v_pk_mul_f32 v[10:11], v[10:11], v[222:223] op_sel_hi:[1,0]
	v_pk_mul_f32 v[12:13], v[12:13], v[222:223] op_sel_hi:[1,0]
	v_pk_mul_f32 v[14:15], v[14:15], v[222:223] op_sel_hi:[1,0]
	v_pk_mul_f32 v[16:17], v[16:17], v[222:223] op_sel_hi:[1,0]
	v_pk_mul_f32 v[18:19], v[18:19], v[222:223] op_sel_hi:[1,0]
	v_pk_mul_f32 v[20:21], v[20:21], v[222:223] op_sel_hi:[1,0]
	v_pk_mul_f32 v[22:23], v[22:23], v[222:223] op_sel_hi:[1,0]
	v_pk_mul_f32 v[24:25], v[24:25], v[222:223] op_sel_hi:[1,0]
	v_pk_mul_f32 v[26:27], v[26:27], v[222:223] op_sel_hi:[1,0]
	v_pk_mul_f32 v[28:29], v[28:29], v[222:223] op_sel_hi:[1,0]
	v_pk_mul_f32 v[30:31], v[30:31], v[222:223] op_sel_hi:[1,0]
	v_pk_mul_f32 v[32:33], v[32:33], v[222:223] op_sel_hi:[1,0]
	v_mul_f32_e32 v170, v170, v222
	v_xor_b32_e32 v82, 0x80000000, v239
	v_mov_b32_e32 v83, v82
	v_mov_b32_e32 v84, v82
	v_mov_b32_e32 v85, v82
	v_mov_b32_e32 v86, v82
	v_mov_b32_e32 v87, v82
	v_mov_b32_e32 v88, v82
	v_mov_b32_e32 v89, v82
	v_mov_b32_e32 v90, v82
	v_mov_b32_e32 v91, v82
	v_mov_b32_e32 v92, v82
	v_mov_b32_e32 v93, v82
	v_mov_b32_e32 v94, v82
	v_mov_b32_e32 v95, v82
	v_mov_b32_e32 v96, v82
	v_mov_b32_e32 v97, v82
	s_nop 1
.LmlaLB_common:
	s_waitcnt lgkmcnt(4)
	v_mfma_f32_32x32x16_bf16 v[66:81], v[172:175], v[150:153], v[82:97]
	ds_read_b128 v[192:195], v164 offset:4608
	s_add_i32 s24, s14, s4
	s_mov_b32 m0, s24
	s_add_u32 s28, s28, 0
	global_load_lds_dwordx4 v154, s[34:35]
	s_add_u32 s34, s34, 0x10000
	s_addc_u32 s35, s35, 0
	v_exp_f32_e32 v98, v98
	v_exp_f32_e32 v99, v99
	v_exp_f32_e32 v100, v100
	s_waitcnt lgkmcnt(4)
	v_mfma_f32_32x32x16_bf16 v[50:65], v[176:179], v[150:153], v[82:97]
	ds_read_b128 v[240:243], v164 offset:6144
	s_add_i32 m0, s24, 0x3000
	s_andn2_b64 vcc, exec, s[16:17]
	global_load_lds_dwordx4 v156, s[28:29]
	s_add_u32 s28, s28, 0x80
	s_addc_u32 s29, s29, 0
	v_exp_f32_e32 v101, v101
	v_exp_f32_e32 v102, v102
	v_exp_f32_e32 v103, v103
	s_waitcnt lgkmcnt(4)
	v_mfma_f32_32x32x16_bf16 v[66:81], v[180:183], v[134:137], v[66:81]
	ds_read_b128 v[244:247], v164 offset:6656
	v_exp_f32_e32 v104, v104
	v_exp_f32_e32 v105, v105
	v_cvt_pk_bf16_f32 v34, v98, v99
	v_cvt_pk_bf16_f32 v35, v100, v101
	s_waitcnt lgkmcnt(4)
	v_mfma_f32_32x32x16_bf16 v[50:65], v[184:187], v[134:137], v[50:65]
	ds_read_b128 v[248:251], v164 offset:8192
	v_exp_f32_e32 v106, v106
	v_exp_f32_e32 v107, v107
	v_cvt_pk_bf16_f32 v36, v102, v103
	v_cvt_pk_bf16_f32 v37, v104, v105
	s_waitcnt lgkmcnt(4)
	v_mfma_f32_32x32x16_bf16 v[66:81], v[188:191], v[138:141], v[66:81]
	ds_read_b128 v[172:175], v164 offset:8704
	s_andn2_b64 vcc, exec, s[16:17]
	s_cbranch_vccnz .LmlaLB_nokr
	s_add_i32 m0, s24, 0x2000
	s_nop 0
	global_load_lds_dwordx4 v158, s[38:39]
.LmlaLB_nokr:
	s_add_u32 s38, s38, 0x10000
	s_addc_u32 s39, s39, 0
	v_exp_f32_e32 v108, v108
	v_exp_f32_e32 v109, v109
	v_exp_f32_e32 v110, v110
	s_waitcnt lgkmcnt(4)
	v_mfma_f32_32x32x16_bf16 v[50:65], v[192:195], v[138:141], v[50:65]
	ds_read_b128 v[176:179], v164 offset:10240
	v_exp_f32_e32 v111, v111
	v_exp_f32_e32 v112, v112
	v_exp_f32_e32 v113, v113
	s_waitcnt lgkmcnt(4)
	v_mfma_f32_32x32x16_bf16 v[66:81], v[240:243], v[142:145], v[66:81]
	ds_read_b128 v[180:183], v164 offset:10752
	v_exp_f32_e32 v114, v114
	v_exp_f32_e32 v115, v115
	v_cvt_pk_bf16_f32 v38, v106, v107
	v_cvt_pk_bf16_f32 v39, v108, v109
	s_waitcnt lgkmcnt(4)
	v_mfma_f32_32x32x16_bf16 v[50:65], v[244:247], v[142:145], v[50:65]
	ds_read_b128 v[184:187], v165 offset:12288
	v_exp_f32_e32 v116, v116
	v_exp_f32_e32 v117, v117
	v_cvt_pk_bf16_f32 v40, v110, v111
	v_cvt_pk_bf16_f32 v41, v112, v113
	s_waitcnt lgkmcnt(4)
	v_mfma_f32_32x32x16_bf16 v[66:81], v[248:251], v[146:149], v[66:81]
	ds_read_b128 v[188:191], v165 offset:12800
	v_exp_f32_e32 v118, v118
	v_exp_f32_e32 v119, v119
	v_exp_f32_e32 v120, v120
	s_waitcnt lgkmcnt(4)
	v_mfma_f32_32x32x16_bf16 v[50:65], v[172:175], v[146:149], v[50:65]
	ds_read_b128 v[192:195], v165 offset:14336
	v_exp_f32_e32 v121, v121
	v_exp_f32_e32 v122, v122
	v_cvt_pk_bf16_f32 v42, v114, v115
	v_cvt_pk_bf16_f32 v43, v116, v117
	s_waitcnt lgkmcnt(4)
	v_mfma_f32_32x32x16_bf16 v[66:81], v[176:179], v[130:133], v[66:81]
	ds_read_b128 v[240:243], v165 offset:14848
	v_exp_f32_e32 v123, v123
	v_exp_f32_e32 v124, v124
	v_cvt_pk_bf16_f32 v44, v118, v119
	v_cvt_pk_bf16_f32 v45, v120, v121
	s_waitcnt lgkmcnt(4)
	v_mfma_f32_32x32x16_bf16 v[50:65], v[180:183], v[130:133], v[50:65]
	ds_read_b128 v[244:247], v165 offset:16384
	v_exp_f32_e32 v125, v125
	v_exp_f32_e32 v126, v126
	v_exp_f32_e32 v127, v127
	s_waitcnt lgkmcnt(4)
	v_mfma_f32_32x32x16_bf16 v[2:17], v[184:187], v[34:37], v[2:17]
	ds_read_b128 v[248:251], v165 offset:16896
	v_exp_f32_e32 v128, v128
	v_exp_f32_e32 v129, v129
	v_cvt_pk_bf16_f32 v46, v122, v123
	v_cvt_pk_bf16_f32 v47, v124, v125
	s_waitcnt lgkmcnt(4)
	v_mfma_f32_32x32x16_bf16 v[18:33], v[188:191], v[34:37], v[18:33]
	ds_read_b128 v[172:175], v165 offset:18432
	v_cvt_pk_bf16_f32 v48, v126, v127
	v_cvt_pk_bf16_f32 v49, v128, v129
	v_add_f32_e32 v166, v98, v99
	v_add_f32_e32 v167, v100, v101
	v_add_f32_e32 v168, v102, v103
	v_add_f32_e32 v169, v104, v105
	s_waitcnt lgkmcnt(4)
	v_mfma_f32_32x32x16_bf16 v[2:17], v[192:195], v[38:41], v[2:17]
	ds_read_b128 v[176:179], v165 offset:18944
	v_add_f32_e32 v166, v166, v106
	v_add_f32_e32 v167, v167, v107
	v_add_f32_e32 v168, v168, v108
	v_add_f32_e32 v169, v169, v109
	v_max3_f32 v162, v66, v67, v68
	v_max3_f32 v163, v50, v51, v52
	s_waitcnt lgkmcnt(4)
	v_mfma_f32_32x32x16_bf16 v[18:33], v[240:243], v[38:41], v[18:33]
	v_add_f32_e32 v166, v166, v110
	v_add_f32_e32 v167, v167, v111
	v_add_f32_e32 v168, v168, v112
	v_add_f32_e32 v169, v169, v113
	v_max3_f32 v162, v162, v69, v70
	v_max3_f32 v163, v163, v53, v54
	s_waitcnt lgkmcnt(3)
	v_mfma_f32_32x32x16_bf16 v[2:17], v[244:247], v[42:45], v[2:17]
	v_add_f32_e32 v166, v166, v114
	v_add_f32_e32 v167, v167, v115
	v_add_f32_e32 v168, v168, v116
	v_add_f32_e32 v169, v169, v117
	v_max3_f32 v162, v162, v71, v72
	v_max3_f32 v163, v163, v55, v56
	s_waitcnt lgkmcnt(2)
	v_mfma_f32_32x32x16_bf16 v[18:33], v[248:251], v[42:45], v[18:33]
	v_add_f32_e32 v166, v166, v118
	v_add_f32_e32 v167, v167, v119
	v_add_f32_e32 v168, v168, v120
	v_add_f32_e32 v169, v169, v121
	v_max3_f32 v162, v162, v73, v74
	v_max3_f32 v163, v163, v57, v58
	s_waitcnt lgkmcnt(1)
	v_mfma_f32_32x32x16_bf16 v[2:17], v[172:175], v[46:49], v[2:17]
	v_add_f32_e32 v166, v166, v122
	v_add_f32_e32 v167, v167, v123
	v_add_f32_e32 v168, v168, v124
	v_add_f32_e32 v169, v169, v125
	v_max3_f32 v162, v162, v75, v76
	v_max3_f32 v163, v163, v59, v60
	s_waitcnt lgkmcnt(0)
	v_mfma_f32_32x32x16_bf16 v[18:33], v[176:179], v[46:49], v[18:33]
	v_add_f32_e32 v166, v166, v126
	v_add_f32_e32 v167, v167, v127
	v_add_f32_e32 v168, v168, v128
	v_add_f32_e32 v169, v169, v129
	v_max3_f32 v162, v162, v77, v78
	v_max3_f32 v163, v163, v61, v62
	v_max3_f32 v162, v162, v79, v80
	v_max3_f32 v163, v163, v63, v64
	v_add_f32_e32 v166, v166, v167
	v_add_f32_e32 v168, v168, v169
	v_add_f32_e32 v166, v166, v168
	v_add_f32_e32 v170, v170, v166
	v_max3_f32 v162, v162, v81, v65
	v_max_f32_e32 v162, v162, v163
	s_add_i32 s19, s19, 2
	s_andn2_b64 vcc, exec, s[16:17]
	s_cbranch_vccnz .LmlaLB_w2
	s_waitcnt vmcnt(3)
	s_branch .LmlaLB_wd

.LmlaS_top:
	v_add_u32_e32 v164, s19, v238
	v_add_u32_e32 v165, s4, v238
	ds_read_b128 v[172:175], v164
	ds_read_b128 v[176:179], v164 offset:512
	ds_read_b128 v[180:183], v164 offset:2048
	ds_read_b128 v[184:187], v164 offset:2560
	ds_read_b128 v[188:191], v164 offset:4096
	s_cmp_eq_u32 s21, -2
	s_cselect_b64 s[6:7], -1, 0
	v_cmp_lt_f32_e32 vcc, s33, v162
	s_or_b64 vcc, s[6:7], vcc
	s_cbranch_vccz .LmlaSA_common
	v_mov_b32_e32 v163, v162
	s_nop 1
	v_permlane32_swap_b32_e32 v162, v163
	v_max_f32_e32 v162, v162, v163
	v_max_f32_e32 v220, 0, v162
	v_cndmask_b32_e64 v220, v220, v162, s[6:7]
	v_exp_f32_e64 v222, -v220
	v_add_f32_e32 v239, v239, v220
	v_pk_add_f32 v[66:67], v[66:67], v[220:221] op_sel_hi:[1,0] neg_lo:[0,1] neg_hi:[0,1]
	v_pk_add_f32 v[68:69], v[68:69], v[220:221] op_sel_hi:[1,0] neg_lo:[0,1] neg_hi:[0,1]
	v_pk_add_f32 v[70:71], v[70:71], v[220:221] op_sel_hi:[1,0] neg_lo:[0,1] neg_hi:[0,1]
	v_pk_add_f32 v[72:73], v[72:73], v[220:221] op_sel_hi:[1,0] neg_lo:[0,1] neg_hi:[0,1]
	v_pk_add_f32 v[74:75], v[74:75], v[220:221] op_sel_hi:[1,0] neg_lo:[0,1] neg_hi:[0,1]
	v_pk_add_f32 v[76:77], v[76:77], v[220:221] op_sel_hi:[1,0] neg_lo:[0,1] neg_hi:[0,1]
	v_pk_add_f32 v[78:79], v[78:79], v[220:221] op_sel_hi:[1,0] neg_lo:[0,1] neg_hi:[0,1]
	v_pk_add_f32 v[80:81], v[80:81], v[220:221] op_sel_hi:[1,0] neg_lo:[0,1] neg_hi:[0,1]
	v_pk_add_f32 v[50:51], v[50:51], v[220:221] op_sel_hi:[1,0] neg_lo:[0,1] neg_hi:[0,1]
	v_pk_add_f32 v[52:53], v[52:53], v[220:221] op_sel_hi:[1,0] neg_lo:[0,1] neg_hi:[0,1]
	v_pk_add_f32 v[54:55], v[54:55], v[220:221] op_sel_hi:[1,0] neg_lo:[0,1] neg_hi:[0,1]
	v_pk_add_f32 v[56:57], v[56:57], v[220:221] op_sel_hi:[1,0] neg_lo:[0,1] neg_hi:[0,1]
	v_pk_add_f32 v[58:59], v[58:59], v[220:221] op_sel_hi:[1,0] neg_lo:[0,1] neg_hi:[0,1]
	v_pk_add_f32 v[60:61], v[60:61], v[220:221] op_sel_hi:[1,0] neg_lo:[0,1] neg_hi:[0,1]
	v_pk_add_f32 v[62:63], v[62:63], v[220:221] op_sel_hi:[1,0] neg_lo:[0,1] neg_hi:[0,1]
	v_pk_add_f32 v[64:65], v[64:65], v[220:221] op_sel_hi:[1,0] neg_lo:[0,1] neg_hi:[0,1]
	v_pk_mul_f32 v[2:3], v[2:3], v[222:223] op_sel_hi:[1,0]
	v_pk_mul_f32 v[4:5], v[4:5], v[222:223] op_sel_hi:[1,0]
	v_pk_mul_f32 v[6:7], v[6:7], v[222:223] op_sel_hi:[1,0]
	v_pk_mul_f32 v[8:9], v[8:9], v[222:223] op_sel_hi:[1,0]
	v_pk_mul_f32 v[10:11], v[10:11], v[222:223] op_sel_hi:[1,0]
	v_pk_mul_f32 v[12:13], v[12:13], v[222:223] op_sel_hi:[1,0]
	v_pk_mul_f32 v[14:15], v[14:15], v[222:223] op_sel_hi:[1,0]
	v_pk_mul_f32 v[16:17], v[16:17], v[222:223] op_sel_hi:[1,0]
	v_pk_mul_f32 v[18:19], v[18:19], v[222:223] op_sel_hi:[1,0]
	v_pk_mul_f32 v[20:21], v[20:21], v[222:223] op_sel_hi:[1,0]
	v_pk_mul_f32 v[22:23], v[22:23], v[222:223] op_sel_hi:[1,0]
	v_pk_mul_f32 v[24:25], v[24:25], v[222:223] op_sel_hi:[1,0]
	v_pk_mul_f32 v[26:27], v[26:27], v[222:223] op_sel_hi:[1,0]
	v_pk_mul_f32 v[28:29], v[28:29], v[222:223] op_sel_hi:[1,0]
	v_pk_mul_f32 v[30:31], v[30:31], v[222:223] op_sel_hi:[1,0]
	v_pk_mul_f32 v[32:33], v[32:33], v[222:223] op_sel_hi:[1,0]
	v_mul_f32_e32 v160, v160, v222
	v_xor_b32_e32 v82, 0x80000000, v239
	v_mov_b32_e32 v83, v82
	v_mov_b32_e32 v84, v82
	v_mov_b32_e32 v85, v82
	v_mov_b32_e32 v86, v82
	v_mov_b32_e32 v87, v82
	v_mov_b32_e32 v88, v82
	v_mov_b32_e32 v89, v82
	v_mov_b32_e32 v90, v82
	v_mov_b32_e32 v91, v82
	v_mov_b32_e32 v92, v82
	v_mov_b32_e32 v93, v82
	v_mov_b32_e32 v94, v82
	v_mov_b32_e32 v95, v82
	v_mov_b32_e32 v96, v82
	v_mov_b32_e32 v97, v82
	s_nop 1
.LmlaSA_common:
	s_waitcnt lgkmcnt(4)
	v_mfma_f32_32x32x16_bf16 v[98:113], v[172:175], v[150:153], v[82:97]
	ds_read_b128 v[192:195], v164 offset:4608
	s_add_i32 s24, s15, s23
	s_mov_b32 m0, s24
	s_add_u32 s28, s28, 0
	global_load_lds_dwordx4 v154, s[34:35]
	s_add_u32 s34, s34, 0x10000
	s_addc_u32 s35, s35, 0
	v_exp_f32_e32 v66, v66
	v_exp_f32_e32 v67, v67
	v_exp_f32_e32 v68, v68
	s_waitcnt lgkmcnt(4)
	v_mfma_f32_32x32x16_bf16 v[114:129], v[176:179], v[150:153], v[82:97]
	ds_read_b128 v[240:243], v164 offset:6144
	s_add_i32 m0, s24, 0x3000
	s_andn2_b64 vcc, exec, s[16:17]
	global_load_lds_dwordx4 v156, s[28:29]
	s_add_u32 s28, s28, 0x80
	s_addc_u32 s29, s29, 0
	v_exp_f32_e32 v69, v69
	v_exp_f32_e32 v70, v70
	v_exp_f32_e32 v71, v71
	s_waitcnt lgkmcnt(4)
	v_mfma_f32_32x32x16_bf16 v[98:113], v[180:183], v[146:149], v[98:113]
	ds_read_b128 v[244:247], v164 offset:6656
	v_exp_f32_e32 v72, v72
	v_exp_f32_e32 v73, v73
	v_cvt_pk_bf16_f32 v34, v66, v67
	v_cvt_pk_bf16_f32 v35, v68, v69
	s_waitcnt lgkmcnt(4)
	v_mfma_f32_32x32x16_bf16 v[114:129], v[184:187], v[146:149], v[114:129]
	ds_read_b128 v[248:251], v164 offset:8192
	v_exp_f32_e32 v74, v74
	v_exp_f32_e32 v75, v75
	v_cvt_pk_bf16_f32 v36, v70, v71
	v_cvt_pk_bf16_f32 v37, v72, v73
	s_waitcnt lgkmcnt(4)
	v_mfma_f32_32x32x16_bf16 v[98:113], v[188:191], v[142:145], v[98:113]
	ds_read_b128 v[172:175], v164 offset:8704
	s_andn2_b64 vcc, exec, s[16:17]
	s_cbranch_vccnz .LmlaSA_nokr
	s_add_i32 m0, s24, 0x2000
	s_nop 0
	global_load_lds_dwordx4 v158, s[38:39]
.LmlaSA_nokr:
	s_add_u32 s38, s38, 0x10000
	s_addc_u32 s39, s39, 0
	v_exp_f32_e32 v76, v76
	v_exp_f32_e32 v77, v77
	v_exp_f32_e32 v78, v78
	s_waitcnt lgkmcnt(4)
	v_mfma_f32_32x32x16_bf16 v[114:129], v[192:195], v[142:145], v[114:129]
	ds_read_b128 v[176:179], v164 offset:10240
	v_exp_f32_e32 v79, v79
	v_exp_f32_e32 v80, v80
	v_exp_f32_e32 v81, v81
	s_waitcnt lgkmcnt(4)
	v_mfma_f32_32x32x16_bf16 v[98:113], v[240:243], v[138:141], v[98:113]
	ds_read_b128 v[180:183], v164 offset:10752
	v_exp_f32_e32 v50, v50
	v_exp_f32_e32 v51, v51
	v_cvt_pk_bf16_f32 v38, v74, v75
	v_cvt_pk_bf16_f32 v39, v76, v77
	s_waitcnt lgkmcnt(4)
	v_mfma_f32_32x32x16_bf16 v[114:129], v[244:247], v[138:141], v[114:129]
	ds_read_b128 v[184:187], v165 offset:12288
	v_exp_f32_e32 v52, v52
	v_exp_f32_e32 v53, v53
	v_cvt_pk_bf16_f32 v40, v78, v79
	v_cvt_pk_bf16_f32 v41, v80, v81
	s_waitcnt lgkmcnt(4)
	v_mfma_f32_32x32x16_bf16 v[98:113], v[248:251], v[134:137], v[98:113]
	ds_read_b128 v[188:191], v165 offset:12800
	v_exp_f32_e32 v54, v54
	v_exp_f32_e32 v55, v55
	v_exp_f32_e32 v56, v56
	s_waitcnt lgkmcnt(4)
	v_mfma_f32_32x32x16_bf16 v[114:129], v[172:175], v[134:137], v[114:129]
	ds_read_b128 v[192:195], v165 offset:14336
	v_exp_f32_e32 v57, v57
	v_exp_f32_e32 v58, v58
	v_cvt_pk_bf16_f32 v42, v50, v51
	v_cvt_pk_bf16_f32 v43, v52, v53
	s_waitcnt lgkmcnt(4)
	v_mfma_f32_32x32x16_bf16 v[98:113], v[176:179], v[130:133], v[98:113]
	ds_read_b128 v[240:243], v165 offset:14848
	v_exp_f32_e32 v59, v59
	v_exp_f32_e32 v60, v60
	v_cvt_pk_bf16_f32 v44, v54, v55
	v_cvt_pk_bf16_f32 v45, v56, v57
	s_waitcnt lgkmcnt(4)
	v_mfma_f32_32x32x16_bf16 v[114:129], v[180:183], v[130:133], v[114:129]
	ds_read_b128 v[244:247], v165 offset:16384
	v_exp_f32_e32 v61, v61
	v_exp_f32_e32 v62, v62
	v_exp_f32_e32 v63, v63
	s_waitcnt lgkmcnt(4)
	v_mfma_f32_32x32x16_bf16 v[2:17], v[184:187], v[34:37], v[2:17]
	ds_read_b128 v[248:251], v165 offset:16896
	v_exp_f32_e32 v64, v64
	v_exp_f32_e32 v65, v65
	v_cvt_pk_bf16_f32 v46, v58, v59
	v_cvt_pk_bf16_f32 v47, v60, v61
	s_waitcnt lgkmcnt(4)
	v_mfma_f32_32x32x16_bf16 v[18:33], v[188:191], v[34:37], v[18:33]
	ds_read_b128 v[172:175], v165 offset:18432
	v_cvt_pk_bf16_f32 v48, v62, v63
	v_cvt_pk_bf16_f32 v49, v64, v65
	v_add_f32_e32 v166, v66, v67
	v_add_f32_e32 v167, v68, v69
	v_add_f32_e32 v168, v70, v71
	v_add_f32_e32 v169, v72, v73
	s_waitcnt lgkmcnt(4)
	v_mfma_f32_32x32x16_bf16 v[2:17], v[192:195], v[38:41], v[2:17]
	ds_read_b128 v[176:179], v165 offset:18944
	v_add_f32_e32 v166, v166, v74
	v_add_f32_e32 v167, v167, v75
	v_add_f32_e32 v168, v168, v76
	v_add_f32_e32 v169, v169, v77
	v_max3_f32 v162, v98, v99, v100
	v_max3_f32 v163, v114, v115, v116
	s_waitcnt lgkmcnt(4)
	v_mfma_f32_32x32x16_bf16 v[18:33], v[240:243], v[38:41], v[18:33]
	v_add_f32_e32 v166, v166, v78
	v_add_f32_e32 v167, v167, v79
	v_add_f32_e32 v168, v168, v80
	v_add_f32_e32 v169, v169, v81
	v_max3_f32 v162, v162, v101, v102
	v_max3_f32 v163, v163, v117, v118
	s_waitcnt lgkmcnt(3)
	v_mfma_f32_32x32x16_bf16 v[2:17], v[244:247], v[42:45], v[2:17]
	v_add_f32_e32 v166, v166, v50
	v_add_f32_e32 v167, v167, v51
	v_add_f32_e32 v168, v168, v52
	v_add_f32_e32 v169, v169, v53
	v_max3_f32 v162, v162, v103, v104
	v_max3_f32 v163, v163, v119, v120
	s_waitcnt lgkmcnt(2)
	v_mfma_f32_32x32x16_bf16 v[18:33], v[248:251], v[42:45], v[18:33]
	v_add_f32_e32 v166, v166, v54
	v_add_f32_e32 v167, v167, v55
	v_add_f32_e32 v168, v168, v56
	v_add_f32_e32 v169, v169, v57
	v_max3_f32 v162, v162, v105, v106
	v_max3_f32 v163, v163, v121, v122
	s_waitcnt lgkmcnt(1)
	v_mfma_f32_32x32x16_bf16 v[2:17], v[172:175], v[46:49], v[2:17]
	v_add_f32_e32 v166, v166, v58
	v_add_f32_e32 v167, v167, v59
	v_add_f32_e32 v168, v168, v60
	v_add_f32_e32 v169, v169, v61
	v_max3_f32 v162, v162, v107, v108
	v_max3_f32 v163, v163, v123, v124
	s_waitcnt lgkmcnt(0)
	v_mfma_f32_32x32x16_bf16 v[18:33], v[176:179], v[46:49], v[18:33]
	v_add_f32_e32 v166, v166, v62
	v_add_f32_e32 v167, v167, v63
	v_add_f32_e32 v168, v168, v64
	v_add_f32_e32 v169, v169, v65
	v_max3_f32 v162, v162, v109, v110
	v_max3_f32 v163, v163, v125, v126
	v_max3_f32 v162, v162, v111, v112
	v_max3_f32 v163, v163, v127, v128
	v_add_f32_e32 v166, v166, v167
	v_add_f32_e32 v168, v168, v169
	v_add_f32_e32 v166, v166, v168
	v_add_f32_e32 v160, v160, v166
	v_max3_f32 v162, v162, v113, v129
	v_max_f32_e32 v162, v162, v163
	s_andn2_b64 vcc, exec, s[16:17]
	s_cbranch_vccnz .LmlaSA_w2
	s_waitcnt vmcnt(3)
	s_branch .LmlaSA_wd

.LmlaSA_wd:
	s_barrier
	v_add_u32_e32 v164, s20, v238
	v_add_u32_e32 v165, s19, v238
	ds_read_b128 v[172:175], v164
	ds_read_b128 v[176:179], v164 offset:512
	ds_read_b128 v[180:183], v164 offset:2048
	ds_read_b128 v[184:187], v164 offset:2560
	ds_read_b128 v[188:191], v164 offset:4096
	v_cmp_lt_f32_e32 vcc, s33, v162
	s_cbranch_vccz .LmlaSB_common
	v_mov_b32_e32 v163, v162
	s_nop 1
	v_permlane32_swap_b32_e32 v162, v163
	v_max_f32_e32 v162, v162, v163
	v_max_f32_e32 v220, 0, v162
	v_exp_f32_e64 v222, -v220
	v_add_f32_e32 v239, v239, v220
	v_pk_add_f32 v[98:99], v[98:99], v[220:221] op_sel_hi:[1,0] neg_lo:[0,1] neg_hi:[0,1]
	v_pk_add_f32 v[100:101], v[100:101], v[220:221] op_sel_hi:[1,0] neg_lo:[0,1] neg_hi:[0,1]
	v_pk_add_f32 v[102:103], v[102:103], v[220:221] op_sel_hi:[1,0] neg_lo:[0,1] neg_hi:[0,1]
	v_pk_add_f32 v[104:105], v[104:105], v[220:221] op_sel_hi:[1,0] neg_lo:[0,1] neg_hi:[0,1]
	v_pk_add_f32 v[106:107], v[106:107], v[220:221] op_sel_hi:[1,0] neg_lo:[0,1] neg_hi:[0,1]
	v_pk_add_f32 v[108:109], v[108:109], v[220:221] op_sel_hi:[1,0] neg_lo:[0,1] neg_hi:[0,1]
	v_pk_add_f32 v[110:111], v[110:111], v[220:221] op_sel_hi:[1,0] neg_lo:[0,1] neg_hi:[0,1]
	v_pk_add_f32 v[112:113], v[112:113], v[220:221] op_sel_hi:[1,0] neg_lo:[0,1] neg_hi:[0,1]
	v_pk_add_f32 v[114:115], v[114:115], v[220:221] op_sel_hi:[1,0] neg_lo:[0,1] neg_hi:[0,1]
	v_pk_add_f32 v[116:117], v[116:117], v[220:221] op_sel_hi:[1,0] neg_lo:[0,1] neg_hi:[0,1]
	v_pk_add_f32 v[118:119], v[118:119], v[220:221] op_sel_hi:[1,0] neg_lo:[0,1] neg_hi:[0,1]
	v_pk_add_f32 v[120:121], v[120:121], v[220:221] op_sel_hi:[1,0] neg_lo:[0,1] neg_hi:[0,1]
	v_pk_add_f32 v[122:123], v[122:123], v[220:221] op_sel_hi:[1,0] neg_lo:[0,1] neg_hi:[0,1]
	v_pk_add_f32 v[124:125], v[124:125], v[220:221] op_sel_hi:[1,0] neg_lo:[0,1] neg_hi:[0,1]
	v_pk_add_f32 v[126:127], v[126:127], v[220:221] op_sel_hi:[1,0] neg_lo:[0,1] neg_hi:[0,1]
	v_pk_add_f32 v[128:129], v[128:129], v[220:221] op_sel_hi:[1,0] neg_lo:[0,1] neg_hi:[0,1]
	v_pk_mul_f32 v[2:3], v[2:3], v[222:223] op_sel_hi:[1,0]
	v_pk_mul_f32 v[4:5], v[4:5], v[222:223] op_sel_hi:[1,0]
	v_pk_mul_f32 v[6:7], v[6:7], v[222:223] op_sel_hi:[1,0]
	v_pk_mul_f32 v[8:9], v[8:9], v[222:223] op_sel_hi:[1,0]
	v_pk_mul_f32 v[10:11], v[10:11], v[222:223] op_sel_hi:[1,0]
	v_pk_mul_f32 v[12:13], v[12:13], v[222:223] op_sel_hi:[1,0]
	v_pk_mul_f32 v[14:15], v[14:15], v[222:223] op_sel_hi:[1,0]
	v_pk_mul_f32 v[16:17], v[16:17], v[222:223] op_sel_hi:[1,0]
	v_pk_mul_f32 v[18:19], v[18:19], v[222:223] op_sel_hi:[1,0]
	v_pk_mul_f32 v[20:21], v[20:21], v[222:223] op_sel_hi:[1,0]
	v_pk_mul_f32 v[22:23], v[22:23], v[222:223] op_sel_hi:[1,0]
	v_pk_mul_f32 v[24:25], v[24:25], v[222:223] op_sel_hi:[1,0]
	v_pk_mul_f32 v[26:27], v[26:27], v[222:223] op_sel_hi:[1,0]
	v_pk_mul_f32 v[28:29], v[28:29], v[222:223] op_sel_hi:[1,0]
	v_pk_mul_f32 v[30:31], v[30:31], v[222:223] op_sel_hi:[1,0]
	v_pk_mul_f32 v[32:33], v[32:33], v[222:223] op_sel_hi:[1,0]
	v_mul_f32_e32 v160, v160, v222
	v_xor_b32_e32 v82, 0x80000000, v239
	v_mov_b32_e32 v83, v82
	v_mov_b32_e32 v84, v82
	v_mov_b32_e32 v85, v82
	v_mov_b32_e32 v86, v82
	v_mov_b32_e32 v87, v82
	v_mov_b32_e32 v88, v82
	v_mov_b32_e32 v89, v82
	v_mov_b32_e32 v90, v82
	v_mov_b32_e32 v91, v82
	v_mov_b32_e32 v92, v82
	v_mov_b32_e32 v93, v82
	v_mov_b32_e32 v94, v82
	v_mov_b32_e32 v95, v82
	v_mov_b32_e32 v96, v82
	v_mov_b32_e32 v97, v82
	s_nop 1
.LmlaSB_common:
	s_waitcnt lgkmcnt(4)
	v_mfma_f32_32x32x16_bf16 v[66:81], v[172:175], v[150:153], v[82:97]
	ds_read_b128 v[192:195], v164 offset:4608
	s_add_i32 s24, s18, s4
	s_mov_b32 m0, s24
	s_add_u32 s28, s28, 0
	global_load_lds_dwordx4 v154, s[34:35]
	s_add_u32 s34, s34, 0x10000
	s_addc_u32 s35, s35, 0
	v_exp_f32_e32 v98, v98
	v_exp_f32_e32 v99, v99
	v_exp_f32_e32 v100, v100
	s_waitcnt lgkmcnt(4)
	v_mfma_f32_32x32x16_bf16 v[50:65], v[176:179], v[150:153], v[82:97]
	ds_read_b128 v[240:243], v164 offset:6144
	s_add_i32 m0, s24, 0x3000
	s_andn2_b64 vcc, exec, s[16:17]
	global_load_lds_dwordx4 v156, s[28:29]
	s_add_u32 s28, s28, 0x80
	s_addc_u32 s29, s29, 0
	v_exp_f32_e32 v101, v101
	v_exp_f32_e32 v102, v102
	v_exp_f32_e32 v103, v103
	s_waitcnt lgkmcnt(4)
	v_mfma_f32_32x32x16_bf16 v[66:81], v[180:183], v[146:149], v[66:81]
	ds_read_b128 v[244:247], v164 offset:6656
	v_exp_f32_e32 v104, v104
	v_exp_f32_e32 v105, v105
	v_cvt_pk_bf16_f32 v34, v98, v99
	v_cvt_pk_bf16_f32 v35, v100, v101
	s_waitcnt lgkmcnt(4)
	v_mfma_f32_32x32x16_bf16 v[50:65], v[184:187], v[146:149], v[50:65]
	ds_read_b128 v[248:251], v164 offset:8192
	v_exp_f32_e32 v106, v106
	v_exp_f32_e32 v107, v107
	v_cvt_pk_bf16_f32 v36, v102, v103
	v_cvt_pk_bf16_f32 v37, v104, v105
	s_waitcnt lgkmcnt(4)
	v_mfma_f32_32x32x16_bf16 v[66:81], v[188:191], v[142:145], v[66:81]
	ds_read_b128 v[172:175], v164 offset:8704
	s_andn2_b64 vcc, exec, s[16:17]
	s_cbranch_vccnz .LmlaSB_nokr
	s_add_i32 m0, s24, 0x2000
	s_nop 0
	global_load_lds_dwordx4 v158, s[38:39]
.LmlaSB_nokr:
	s_add_u32 s38, s38, 0x10000
	s_addc_u32 s39, s39, 0
	v_exp_f32_e32 v108, v108
	v_exp_f32_e32 v109, v109
	v_exp_f32_e32 v110, v110
	s_waitcnt lgkmcnt(4)
	v_mfma_f32_32x32x16_bf16 v[50:65], v[192:195], v[142:145], v[50:65]
	ds_read_b128 v[176:179], v164 offset:10240
	v_exp_f32_e32 v111, v111
	v_exp_f32_e32 v112, v112
	v_exp_f32_e32 v113, v113
	s_waitcnt lgkmcnt(4)
	v_mfma_f32_32x32x16_bf16 v[66:81], v[240:243], v[138:141], v[66:81]
	ds_read_b128 v[180:183], v164 offset:10752
	v_exp_f32_e32 v114, v114
	v_exp_f32_e32 v115, v115
	v_cvt_pk_bf16_f32 v38, v106, v107
	v_cvt_pk_bf16_f32 v39, v108, v109
	s_waitcnt lgkmcnt(4)
	v_mfma_f32_32x32x16_bf16 v[50:65], v[244:247], v[138:141], v[50:65]
	ds_read_b128 v[184:187], v165 offset:12288
	v_exp_f32_e32 v116, v116
	v_exp_f32_e32 v117, v117
	v_cvt_pk_bf16_f32 v40, v110, v111
	v_cvt_pk_bf16_f32 v41, v112, v113
	s_waitcnt lgkmcnt(4)
	v_mfma_f32_32x32x16_bf16 v[66:81], v[248:251], v[134:137], v[66:81]
	ds_read_b128 v[188:191], v165 offset:12800
	v_exp_f32_e32 v118, v118
	v_exp_f32_e32 v119, v119
	v_exp_f32_e32 v120, v120
	s_waitcnt lgkmcnt(4)
	v_mfma_f32_32x32x16_bf16 v[50:65], v[172:175], v[134:137], v[50:65]
	ds_read_b128 v[192:195], v165 offset:14336
	v_exp_f32_e32 v121, v121
	v_exp_f32_e32 v122, v122
	v_cvt_pk_bf16_f32 v42, v114, v115
	v_cvt_pk_bf16_f32 v43, v116, v117
	s_waitcnt lgkmcnt(4)
	v_mfma_f32_32x32x16_bf16 v[66:81], v[176:179], v[130:133], v[66:81]
	ds_read_b128 v[240:243], v165 offset:14848
	v_exp_f32_e32 v123, v123
	v_exp_f32_e32 v124, v124
	v_cvt_pk_bf16_f32 v44, v118, v119
	v_cvt_pk_bf16_f32 v45, v120, v121
	s_waitcnt lgkmcnt(4)
	v_mfma_f32_32x32x16_bf16 v[50:65], v[180:183], v[130:133], v[50:65]
	ds_read_b128 v[244:247], v165 offset:16384
	v_exp_f32_e32 v125, v125
	v_exp_f32_e32 v126, v126
	v_exp_f32_e32 v127, v127
	s_waitcnt lgkmcnt(4)
	v_mfma_f32_32x32x16_bf16 v[2:17], v[184:187], v[34:37], v[2:17]
	ds_read_b128 v[248:251], v165 offset:16896
	v_exp_f32_e32 v128, v128
	v_exp_f32_e32 v129, v129
	v_cvt_pk_bf16_f32 v46, v122, v123
	v_cvt_pk_bf16_f32 v47, v124, v125
	s_waitcnt lgkmcnt(4)
	v_mfma_f32_32x32x16_bf16 v[18:33], v[188:191], v[34:37], v[18:33]
	ds_read_b128 v[172:175], v165 offset:18432
	v_cvt_pk_bf16_f32 v48, v126, v127
	v_cvt_pk_bf16_f32 v49, v128, v129
	v_add_f32_e32 v166, v98, v99
	v_add_f32_e32 v167, v100, v101
	v_add_f32_e32 v168, v102, v103
	v_add_f32_e32 v169, v104, v105
	s_waitcnt lgkmcnt(4)
	v_mfma_f32_32x32x16_bf16 v[2:17], v[192:195], v[38:41], v[2:17]
	ds_read_b128 v[176:179], v165 offset:18944
	v_add_f32_e32 v166, v166, v106
	v_add_f32_e32 v167, v167, v107
	v_add_f32_e32 v168, v168, v108
	v_add_f32_e32 v169, v169, v109
	v_max3_f32 v162, v66, v67, v68
	v_max3_f32 v163, v50, v51, v52
	s_waitcnt lgkmcnt(4)
	v_mfma_f32_32x32x16_bf16 v[18:33], v[240:243], v[38:41], v[18:33]
	v_add_f32_e32 v166, v166, v110
	v_add_f32_e32 v167, v167, v111
	v_add_f32_e32 v168, v168, v112
	v_add_f32_e32 v169, v169, v113
	v_max3_f32 v162, v162, v69, v70
	v_max3_f32 v163, v163, v53, v54
	s_waitcnt lgkmcnt(3)
	v_mfma_f32_32x32x16_bf16 v[2:17], v[244:247], v[42:45], v[2:17]
	v_add_f32_e32 v166, v166, v114
	v_add_f32_e32 v167, v167, v115
	v_add_f32_e32 v168, v168, v116
	v_add_f32_e32 v169, v169, v117
	v_max3_f32 v162, v162, v71, v72
	v_max3_f32 v163, v163, v55, v56
	s_waitcnt lgkmcnt(2)
	v_mfma_f32_32x32x16_bf16 v[18:33], v[248:251], v[42:45], v[18:33]
	v_add_f32_e32 v166, v166, v118
	v_add_f32_e32 v167, v167, v119
	v_add_f32_e32 v168, v168, v120
	v_add_f32_e32 v169, v169, v121
	v_max3_f32 v162, v162, v73, v74
	v_max3_f32 v163, v163, v57, v58
	s_waitcnt lgkmcnt(1)
	v_mfma_f32_32x32x16_bf16 v[2:17], v[172:175], v[46:49], v[2:17]
	v_add_f32_e32 v166, v166, v122
	v_add_f32_e32 v167, v167, v123
	v_add_f32_e32 v168, v168, v124
	v_add_f32_e32 v169, v169, v125
	v_max3_f32 v162, v162, v75, v76
	v_max3_f32 v163, v163, v59, v60
	s_waitcnt lgkmcnt(0)
	v_mfma_f32_32x32x16_bf16 v[18:33], v[176:179], v[46:49], v[18:33]
	v_add_f32_e32 v166, v166, v126
	v_add_f32_e32 v167, v167, v127
	v_add_f32_e32 v168, v168, v128
	v_add_f32_e32 v169, v169, v129
	v_max3_f32 v162, v162, v77, v78
	v_max3_f32 v163, v163, v61, v62
	v_max3_f32 v162, v162, v79, v80
	v_max3_f32 v163, v163, v63, v64
	v_add_f32_e32 v166, v166, v167
	v_add_f32_e32 v168, v168, v169
	v_add_f32_e32 v166, v166, v168
	v_add_f32_e32 v160, v160, v166
	v_max3_f32 v162, v162, v81, v65
	v_max_f32_e32 v162, v162, v163
	s_add_i32 s21, s21, 2
	s_andn2_b64 vcc, exec, s[16:17]
	s_cbranch_vccnz .LmlaSB_w2
	s_waitcnt vmcnt(3)
	s_branch .LmlaSB_wd
